# grid-barrier poll loops: s_sleep 1 removed at 37 sites (tighter polling), on top of the unrolled ctx-silu loop and p_mods wide batch
# speedup vs baseline: 1.0045x; 1.0030x over previous
; __global__ void __launch_bounds__(NTHR, 2) fwd_megakernel(Args a) {
;     ...
;     if (gridDim.x == 0x7fffffffu) grid.sync();
.LBB0_37:
	global_load_dword v2, v0, s[6:7] offset:32 sc1
	s_waitcnt vmcnt(0)
	v_and_b32_e32 v2, 0xffff0000, v2
	v_cmp_ne_u32_e32 vcc, v2, v1
	s_or_b64 s[8:9], vcc, s[8:9]
	s_andn2_b64 exec, exec, s[8:9]
	s_cbranch_execnz .LBB0_37

; __device__ __forceinline__ unsigned xb_ld(unsigned* p)              { return __hip_atomic_load(p, __ATOMIC_RELAXED, __HIP_MEMORY_SCOPE_AGENT); }
; __device__ __forceinline__ void xcd_barrier_complete(unsigned* bar, unsigned x, unsigned& nloc, unsigned& nx) {
;     const unsigned G = gridDim.x * gridDim.y * gridDim.z;
;     unsigned sum, cnt, mine, sp = 0u;
;     for (;;) {
;         sum = 0u; cnt = 0u; mine = 0u;
; #pragma unroll
;         for (unsigned j = 0; j < 16; ++j) { const unsigned c = xb_ld(&bar[XB_XCNT(j)]); sum += c; cnt += (c > 0u) ? 1u : 0u; mine = (j == x) ? c : mine; }
;         if (sum == G) break;
;         __builtin_amdgcn_s_sleep(1);
;         if ((++sp & 255u) == 0u) { if (xb_ld(&bar[XB_TMO])) break; if (sp > XB_SPIN_CAP) { atomicAdd(&bar[XB_TMO], 1u); break; } }
;     }
;     nloc = mine > 0u ? mine : 1u; nx = cnt > 0u ? cnt : 1u;
; }
.LBB0_44:
	v_readlane_b32 s4, v253, 45
	v_readlane_b32 s5, v253, 46
	global_load_dword v3, v16, s[74:75] sc1
	s_waitcnt lgkmcnt(0)
	global_load_dword v0, v16, s[82:83] sc1
	global_load_dword v1, v16, s[90:91] sc1
	global_load_dword v2, v16, s[50:51] sc1
	v_readlane_b32 s6, v253, 44
	global_load_dword v4, v16, s[4:5] sc1
	v_readlane_b32 s4, v253, 47
	v_readlane_b32 s5, v253, 48
	s_nop 4
	global_load_dword v5, v16, s[4:5] sc1
	global_load_dword v6, v16, s[84:85] sc1
	global_load_dword v7, v16, s[86:87] sc1
	global_load_dword v8, v16, s[20:21] sc1
	global_load_dword v9, v16, s[48:49] sc1
	global_load_dword v10, v16, s[88:89] sc1
	v_readlane_b32 s4, v253, 49
	v_readlane_b32 s5, v253, 50
	s_waitcnt vmcnt(9)
	v_add_u32_e32 v17, v0, v3
	s_nop 2
	global_load_dword v11, v16, s[4:5] sc1
	v_readlane_b32 s4, v253, 51
	v_readlane_b32 s5, v253, 52
	s_waitcnt vmcnt(9)
	v_add_u32_e32 v17, v17, v1
	s_waitcnt vmcnt(8)
	v_add_u32_e32 v17, v17, v2
	s_waitcnt vmcnt(7)
	v_add_u32_e32 v17, v17, v4
	s_waitcnt vmcnt(6)
	v_add_u32_e32 v17, v17, v5
	s_waitcnt vmcnt(5)
	v_add_u32_e32 v17, v17, v6
	global_load_dword v12, v16, s[4:5] sc1
	v_readlane_b32 s4, v253, 53
	v_readlane_b32 s5, v253, 54
	s_waitcnt vmcnt(5)
	v_add_u32_e32 v17, v17, v7
	s_waitcnt vmcnt(4)
	v_add_u32_e32 v17, v17, v8
	s_waitcnt vmcnt(3)
	v_add_u32_e32 v17, v17, v9
	s_waitcnt vmcnt(2)
	v_add_u32_e32 v17, v17, v10
	s_waitcnt vmcnt(1)
	v_add_u32_e32 v17, v17, v11
	global_load_dword v13, v16, s[4:5] sc1
	v_readlane_b32 s4, v253, 55
	v_readlane_b32 s5, v253, 56
	s_waitcnt vmcnt(1)
	v_add_u32_e32 v17, v17, v12
	s_nop 2
	global_load_dword v14, v16, s[4:5] sc1
	v_readlane_b32 s4, v253, 57
	v_readlane_b32 s5, v253, 58
	s_waitcnt vmcnt(1)
	v_add_u32_e32 v17, v17, v13
	s_nop 2
	global_load_dword v15, v16, s[4:5] sc1
	s_mov_b64 s[4:5], -1
	s_waitcnt vmcnt(1)
	v_add_u32_e32 v17, v17, v14
	s_waitcnt vmcnt(0)
	v_add_u32_e32 v17, v17, v15
	v_cmp_eq_u32_e32 vcc, s6, v17
	s_mov_b64 s[6:7], -1
	s_cbranch_vccnz .LBB0_43
	s_and_b32 s4, s3, 0xff
	s_cmp_eq_u32 s4, 0
	s_mov_b64 s[4:5], -1
	s_mov_b64 s[8:9], -1
	s_cbranch_scc1 .LBB0_48
	s_and_b64 vcc, exec, s[8:9]
	s_cbranch_vccz .LBB0_43

.LBB0_62:
	s_and_b32 s14, s3, 0xff
	s_mov_b64 s[12:13], -1
	s_cmp_lg_u32 s14, 0
	s_mov_b64 s[16:17], -1
	s_cbranch_scc0 .LBB0_65
	s_and_b64 vcc, exec, s[16:17]
	s_cbranch_vccz .LBB0_61

.LBB0_79:
	s_and_b32 s12, s3, 0xff
	s_cmp_lg_u32 s12, 0
	s_mov_b64 s[14:15], -1
	s_cbranch_scc0 .LBB0_82
	s_mov_b64 s[16:17], -1
	s_and_b64 vcc, exec, s[14:15]
	s_cbranch_vccz .LBB0_78

; __device__ __forceinline__ unsigned xb_ld(unsigned* p)              { return __hip_atomic_load(p, __ATOMIC_RELAXED, __HIP_MEMORY_SCOPE_AGENT); }
; __device__ __forceinline__ void xcd_barrier_complete(unsigned* bar, unsigned x, unsigned& nloc, unsigned& nx) {
;     ...
;     for (;;) {
;         sum = 0u; cnt = 0u; mine = 0u;
; #pragma unroll
;         for (unsigned j = 0; j < 16; ++j) { const unsigned c = xb_ld(&bar[XB_XCNT(j)]); sum += c; cnt += (c > 0u) ? 1u : 0u; mine = (j == x) ? c : mine; }
;         if (sum == G) break;
;         __builtin_amdgcn_s_sleep(1);
;         if ((++sp & 255u) == 0u) { if (xb_ld(&bar[XB_TMO])) break; if (sp > XB_SPIN_CAP) { atomicAdd(&bar[XB_TMO], 1u); break; } }
;     }
.LBB0_144:
	v_readlane_b32 s2, v253, 49
	v_readlane_b32 s3, v253, 50
	global_load_dword v11, v1, s[74:75] sc1
	global_load_dword v0, v1, s[82:83] sc1
	s_waitcnt lgkmcnt(0)
	global_load_dword v2, v1, s[90:91] sc1
	global_load_dword v3, v1, s[50:51] sc1
	global_load_dword v4, v1, s[38:39] sc1
	global_load_dword v5, v1, s[52:53] sc1
	global_load_dword v6, v1, s[84:85] sc1
	global_load_dword v7, v1, s[86:87] sc1
	global_load_dword v8, v1, s[20:21] sc1
	global_load_dword v9, v1, s[48:49] sc1
	global_load_dword v10, v1, s[88:89] sc1
	global_load_dword v12, v1, s[2:3] sc1
	v_readlane_b32 s2, v253, 51
	v_readlane_b32 s3, v253, 52
	v_readlane_b32 s4, v253, 44
	s_waitcnt vmcnt(10)
	v_add_u32_e32 v17, v0, v11
	s_nop 1
	global_load_dword v13, v1, s[2:3] sc1
	v_readlane_b32 s2, v253, 53
	v_readlane_b32 s3, v253, 54
	s_waitcnt vmcnt(10)
	v_add_u32_e32 v17, v17, v2
	s_waitcnt vmcnt(9)
	v_add_u32_e32 v17, v17, v3
	s_waitcnt vmcnt(8)
	v_add_u32_e32 v17, v17, v4
	s_waitcnt vmcnt(7)
	v_add_u32_e32 v17, v17, v5
	s_waitcnt vmcnt(6)
	v_add_u32_e32 v17, v17, v6
	global_load_dword v14, v1, s[2:3] sc1
	v_readlane_b32 s2, v253, 55
	v_readlane_b32 s3, v253, 56
	s_waitcnt vmcnt(6)
	v_add_u32_e32 v17, v17, v7
	s_waitcnt vmcnt(5)
	v_add_u32_e32 v17, v17, v8
	s_waitcnt vmcnt(4)
	v_add_u32_e32 v17, v17, v9
	s_waitcnt vmcnt(3)
	v_add_u32_e32 v17, v17, v10
	s_waitcnt vmcnt(2)
	v_add_u32_e32 v17, v17, v12
	global_load_dword v15, v1, s[2:3] sc1
	v_readlane_b32 s2, v253, 57
	v_readlane_b32 s3, v253, 58
	s_waitcnt vmcnt(2)
	v_add_u32_e32 v17, v17, v13
	s_nop 2
	global_load_dword v16, v1, s[2:3] sc1
	s_mov_b64 s[2:3], -1
	s_waitcnt vmcnt(2)
	v_add_u32_e32 v17, v17, v14
	s_waitcnt vmcnt(1)
	v_add_u32_e32 v17, v17, v15
	s_waitcnt vmcnt(0)
	v_add_u32_e32 v17, v17, v16
	v_cmp_eq_u32_e32 vcc, s4, v17
	s_mov_b64 s[4:5], -1
	s_cbranch_vccnz .LBB0_143
	s_and_b32 s2, s8, 0xff
	s_cmp_eq_u32 s2, 0
	s_mov_b64 s[2:3], -1
	s_mov_b64 s[6:7], -1
	s_cbranch_scc1 .LBB0_148
	s_and_b64 vcc, exec, s[6:7]
	s_cbranch_vccz .LBB0_143

.LBB0_162:
	s_and_b32 s16, s20, 0xff
	s_mov_b64 s[10:11], -1
	s_cmp_lg_u32 s16, 0
	s_mov_b64 s[18:19], -1
	s_cbranch_scc0 .LBB0_165
	s_and_b64 vcc, exec, s[18:19]
	s_cbranch_vccz .LBB0_161

; __device__ __forceinline__ unsigned xb_ld(unsigned* p)              { return __hip_atomic_load(p, __ATOMIC_RELAXED, __HIP_MEMORY_SCOPE_AGENT); }
; __device__ __forceinline__ void xcd_barrier_complete(unsigned* bar, unsigned x, unsigned& nloc, unsigned& nx) {
;     ...
;     for (;;) {
;         sum = 0u; cnt = 0u; mine = 0u;
; #pragma unroll
;         for (unsigned j = 0; j < 16; ++j) { const unsigned c = xb_ld(&bar[XB_XCNT(j)]); sum += c; cnt += (c > 0u) ? 1u : 0u; mine = (j == x) ? c : mine; }
;         if (sum == G) break;
;         __builtin_amdgcn_s_sleep(1);
;         if ((++sp & 255u) == 0u) { if (xb_ld(&bar[XB_TMO])) break; if (sp > XB_SPIN_CAP) { atomicAdd(&bar[XB_TMO], 1u); break; } }
;     }
.LBB0_1020:
	v_readlane_b32 s6, v253, 49
	v_readlane_b32 s7, v253, 50
	global_load_dword v11, v1, s[74:75] sc1
	global_load_dword v0, v1, s[82:83] sc1
	s_waitcnt lgkmcnt(0)
	global_load_dword v2, v1, s[90:91] sc1
	global_load_dword v3, v1, s[50:51] sc1
	global_load_dword v4, v1, s[38:39] sc1
	global_load_dword v5, v1, s[52:53] sc1
	global_load_dword v6, v1, s[84:85] sc1
	global_load_dword v7, v1, s[86:87] sc1
	global_load_dword v8, v1, s[20:21] sc1
	global_load_dword v9, v1, s[48:49] sc1
	global_load_dword v10, v1, s[88:89] sc1
	global_load_dword v12, v1, s[6:7] sc1
	v_readlane_b32 s6, v253, 51
	v_readlane_b32 s7, v253, 52
	v_readlane_b32 s8, v253, 44
	s_waitcnt vmcnt(10)
	v_add_u32_e32 v17, v0, v11
	s_nop 1
	global_load_dword v13, v1, s[6:7] sc1
	v_readlane_b32 s6, v253, 53
	v_readlane_b32 s7, v253, 54
	s_waitcnt vmcnt(10)
	v_add_u32_e32 v17, v17, v2
	s_waitcnt vmcnt(9)
	v_add_u32_e32 v17, v17, v3
	s_waitcnt vmcnt(8)
	v_add_u32_e32 v17, v17, v4
	s_waitcnt vmcnt(7)
	v_add_u32_e32 v17, v17, v5
	s_waitcnt vmcnt(6)
	v_add_u32_e32 v17, v17, v6
	global_load_dword v14, v1, s[6:7] sc1
	v_readlane_b32 s6, v253, 55
	v_readlane_b32 s7, v253, 56
	s_waitcnt vmcnt(6)
	v_add_u32_e32 v17, v17, v7
	s_waitcnt vmcnt(5)
	v_add_u32_e32 v17, v17, v8
	s_waitcnt vmcnt(4)
	v_add_u32_e32 v17, v17, v9
	s_waitcnt vmcnt(3)
	v_add_u32_e32 v17, v17, v10
	s_waitcnt vmcnt(2)
	v_add_u32_e32 v17, v17, v12
	global_load_dword v15, v1, s[6:7] sc1
	v_readlane_b32 s6, v253, 57
	v_readlane_b32 s7, v253, 58
	s_waitcnt vmcnt(2)
	v_add_u32_e32 v17, v17, v13
	s_nop 2
	global_load_dword v16, v1, s[6:7] sc1
	s_mov_b64 s[6:7], -1
	s_waitcnt vmcnt(2)
	v_add_u32_e32 v17, v17, v14
	s_waitcnt vmcnt(1)
	v_add_u32_e32 v17, v17, v15
	s_waitcnt vmcnt(0)
	v_add_u32_e32 v17, v17, v16
	v_cmp_eq_u32_e32 vcc, s8, v17
	s_mov_b64 s[8:9], -1
	s_cbranch_vccnz .LBB0_1019
	s_and_b32 s6, s16, 0xff
	s_cmp_eq_u32 s6, 0
	s_mov_b64 s[6:7], -1
	s_mov_b64 s[10:11], -1
	s_cbranch_scc1 .LBB0_1024
	s_and_b64 vcc, exec, s[10:11]
	s_cbranch_vccz .LBB0_1019

.LBB0_1038:
	s_and_b32 s20, s24, 0xff
	s_mov_b64 s[18:19], -1
	s_cmp_lg_u32 s20, 0
	s_mov_b64 s[22:23], -1
	s_cbranch_scc0 .LBB0_1041
	s_and_b64 vcc, exec, s[22:23]
	s_cbranch_vccz .LBB0_1037
